# v69 + dn_pre forward substitution: 4 rank-4 f32-MFMA updates per pass with LDS reads issued up front
# speedup vs baseline: 1.0115x; 1.0048x over previous
.LBB0_423:
	ds_read_b32 v44, v19
	ds_read_b32 v45, v19 offset:1088
	ds_read_b32 v46, v19 offset:2176
	ds_read_b32 v47, v19 offset:3264
	ds_read_b32 v48, v20
	ds_read_b32 v49, v20 offset:64
	ds_read_b32 v50, v20 offset:2112
	ds_read_b32 v51, v20 offset:2176
	ds_read_b32 v52, v20 offset:4224
	ds_read_b32 v53, v20 offset:4288
	ds_read_b32 v54, v20 offset:6336
	ds_read_b32 v55, v20 offset:6400
	s_add_i32 s37, s37, -4
	v_add_u32_e32 v20, 0x2100, v20
	v_add_u32_e32 v19, 0x1100, v19
	s_waitcnt lgkmcnt(8)
	v_xor_b32_e32 v44, 0x80000000, v44
	v_xor_b32_e32 v45, 0x80000000, v45
	v_xor_b32_e32 v46, 0x80000000, v46
	v_xor_b32_e32 v47, 0x80000000, v47
	s_waitcnt lgkmcnt(6)
	v_mfma_f32_16x16x4_f32 v[4:7], v44, v48, v[4:7]
	v_mfma_f32_16x16x4_f32 v[8:11], v44, v49, v[8:11]
	s_waitcnt lgkmcnt(4)
	v_mfma_f32_16x16x4_f32 v[4:7], v45, v50, v[4:7]
	v_mfma_f32_16x16x4_f32 v[8:11], v45, v51, v[8:11]
	s_waitcnt lgkmcnt(2)
	v_mfma_f32_16x16x4_f32 v[4:7], v46, v52, v[4:7]
	v_mfma_f32_16x16x4_f32 v[8:11], v46, v53, v[8:11]
	s_cmp_eq_u32 s37, 0
	s_waitcnt lgkmcnt(0)
	v_mfma_f32_16x16x4_f32 v[4:7], v47, v54, v[4:7]
	v_mfma_f32_16x16x4_f32 v[8:11], v47, v55, v[8:11]
	s_cbranch_scc0 .LBB0_423
	s_branch .LBB0_420
